# grid barrier release flattened: XCD-last arriver bumps a per-XCC flag in one shared 64-byte line; every workgroup polls that line directly with one 16-lane load (no top counter, no per-XCD generation
# baseline (speedup 1.0000x reference)
.LBB0_298:
	s_or_b64 exec, exec, s[12:13]
	v_cvt_f32_u32_e32 v4, v2
	s_waitcnt vmcnt(0)
	v_readfirstlane_b32 s2, v3
	v_sub_u32_e32 v3, 0, v2
	v_rcp_iflag_f32_e32 v4, v4
	v_add_u32_e32 v5, s2, v1
	v_mul_f32_e32 v4, 0x4f7ffffe, v4
	v_cvt_u32_f32_e32 v4, v4
	v_mul_lo_u32 v1, v3, v4
	v_mul_hi_u32 v1, v4, v1
	v_add_u32_e32 v1, v4, v1
	v_mul_hi_u32 v1, v5, v1
	v_mul_lo_u32 v3, v1, v2
	v_sub_u32_e32 v3, v5, v3
	v_add_u32_e32 v4, 1, v1
	v_cmp_ge_u32_e32 vcc, v3, v2
	s_nop 1
	v_cndmask_b32_e32 v1, v1, v4, vcc
	v_sub_u32_e32 v4, v3, v2
	v_cndmask_b32_e32 v3, v3, v4, vcc
	v_add_u32_e32 v4, 1, v1
	v_cmp_ge_u32_e32 vcc, v3, v2
	v_add_u32_e32 v3, 1, v5
	s_nop 0
	v_cndmask_b32_e32 v1, v1, v4, vcc
	v_mul_lo_u32 v4, v2, v1
	v_add_u32_e32 v2, v4, v2
	v_cmp_eq_u32_e32 vcc, v3, v2
	s_and_saveexec_b64 s[10:11], vcc
	s_cbranch_execz .Lfb_nl_0
	s_sub_u32 s100, s6, s4
	s_sub_u32 s100, s100, 0x4000
	s_lshr_b32 s100, s100, 6
	s_add_u32 s100, s100, 0x8000
	v_mov_b32_e32 v4, s100
	v_mov_b32_e32 v5, 1
	global_atomic_add v4, v5, s[4:5]
.Lfb_nl_0:
	s_or_b64 exec, exec, s[10:11]
	s_waitcnt lgkmcnt(0)
	s_nop 0
	v_readfirstlane_b32 s100, v1
	v_readfirstlane_b32 s101, v0
	s_mov_b32 s10, 0
	s_mov_b64 exec, 0xffff
	v_mbcnt_lo_u32_b32 v2, -1, 0
	v_lshlrev_b32_e32 v2, 2, v2
	v_add_u32_e32 v2, 0x8000, v2
.Lfb_poll_0:
	global_load_dword v3, v2, s[4:5] sc1
	s_waitcnt vmcnt(0)
	v_cmp_le_u32_e32 vcc, s100, v3
	s_bcnt1_i32_b32 vcc_hi, vcc_lo
	s_cmp_ge_u32 vcc_hi, s101
	s_cbranch_scc1 .Lfb_done_0
	s_sleep 1
	s_add_u32 s10, s10, 1
	s_cmp_lt_u32 s10, 0x40000
	s_cbranch_scc1 .Lfb_poll_0
.Lfb_done_0:
	s_mov_b64 exec, 1

.LBB0_403:
	s_or_b64 exec, exec, s[12:13]
	v_cvt_f32_u32_e32 v4, v2
	s_waitcnt vmcnt(0)
	v_readfirstlane_b32 s10, v3
	v_sub_u32_e32 v3, 0, v2
	v_rcp_iflag_f32_e32 v4, v4
	v_add_u32_e32 v5, s10, v1
	v_mul_f32_e32 v4, 0x4f7ffffe, v4
	v_cvt_u32_f32_e32 v4, v4
	v_mul_lo_u32 v1, v3, v4
	v_mul_hi_u32 v1, v4, v1
	v_add_u32_e32 v1, v4, v1
	v_mul_hi_u32 v1, v5, v1
	v_mul_lo_u32 v3, v1, v2
	v_sub_u32_e32 v3, v5, v3
	v_add_u32_e32 v4, 1, v1
	v_cmp_ge_u32_e32 vcc, v3, v2
	s_nop 1
	v_cndmask_b32_e32 v1, v1, v4, vcc
	v_sub_u32_e32 v4, v3, v2
	v_cndmask_b32_e32 v3, v3, v4, vcc
	v_add_u32_e32 v4, 1, v1
	v_cmp_ge_u32_e32 vcc, v3, v2
	v_add_u32_e32 v3, 1, v5
	s_nop 0
	v_cndmask_b32_e32 v1, v1, v4, vcc
	v_mul_lo_u32 v4, v2, v1
	v_add_u32_e32 v2, v4, v2
	v_cmp_eq_u32_e32 vcc, v3, v2
	s_and_saveexec_b64 s[10:11], vcc
	s_cbranch_execz .Lfb_nl_1
	s_sub_u32 s100, s6, s4
	s_sub_u32 s100, s100, 0x4000
	s_lshr_b32 s100, s100, 6
	s_add_u32 s100, s100, 0x8000
	v_mov_b32_e32 v4, s100
	v_mov_b32_e32 v5, 1
	global_atomic_add v4, v5, s[4:5]

.LBB0_484:
	s_or_b64 exec, exec, s[14:15]
	v_cvt_f32_u32_e32 v4, v2
	s_waitcnt vmcnt(0)
	v_readfirstlane_b32 s2, v3
	v_sub_u32_e32 v3, 0, v2
	v_rcp_iflag_f32_e32 v4, v4
	v_add_u32_e32 v5, s2, v1
	v_mul_f32_e32 v4, 0x4f7ffffe, v4
	v_cvt_u32_f32_e32 v4, v4
	v_mul_lo_u32 v1, v3, v4
	v_mul_hi_u32 v1, v4, v1
	v_add_u32_e32 v1, v4, v1
	v_mul_hi_u32 v1, v5, v1
	v_mul_lo_u32 v3, v1, v2
	v_sub_u32_e32 v3, v5, v3
	v_add_u32_e32 v4, 1, v1
	v_cmp_ge_u32_e32 vcc, v3, v2
	s_nop 1
	v_cndmask_b32_e32 v1, v1, v4, vcc
	v_sub_u32_e32 v4, v3, v2
	v_cndmask_b32_e32 v3, v3, v4, vcc
	v_add_u32_e32 v4, 1, v1
	v_cmp_ge_u32_e32 vcc, v3, v2
	v_add_u32_e32 v3, 1, v5
	s_nop 0
	v_cndmask_b32_e32 v1, v1, v4, vcc
	v_mul_lo_u32 v4, v2, v1
	v_add_u32_e32 v2, v4, v2
	v_cmp_eq_u32_e32 vcc, v3, v2
	s_and_saveexec_b64 s[12:13], vcc
	s_cbranch_execz .Lfb_nl_2
	s_sub_u32 s100, s8, s6
	s_sub_u32 s100, s100, 0x4000
	s_lshr_b32 s100, s100, 6
	s_add_u32 s100, s100, 0x8000
	v_mov_b32_e32 v4, s100
	v_mov_b32_e32 v5, 1
	global_atomic_add v4, v5, s[6:7]
.Lfb_nl_2:
	s_or_b64 exec, exec, s[12:13]
	s_waitcnt lgkmcnt(0)
	s_nop 0
	v_readfirstlane_b32 s100, v1
	v_readfirstlane_b32 s101, v0
	s_mov_b32 s12, 0
	s_mov_b64 exec, 0xffff
	v_mbcnt_lo_u32_b32 v2, -1, 0
	v_lshlrev_b32_e32 v2, 2, v2
	v_add_u32_e32 v2, 0x8000, v2
.Lfb_poll_2:
	global_load_dword v3, v2, s[6:7] sc1
	s_waitcnt vmcnt(0)
	v_cmp_le_u32_e32 vcc, s100, v3
	s_bcnt1_i32_b32 vcc_hi, vcc_lo
	s_cmp_ge_u32 vcc_hi, s101
	s_cbranch_scc1 .Lfb_done_2
	s_sleep 1
	s_add_u32 s12, s12, 1
	s_cmp_lt_u32 s12, 0x40000
	s_cbranch_scc1 .Lfb_poll_2

.LBB0_541:
	s_or_b64 exec, exec, s[12:13]
	v_cvt_f32_u32_e32 v4, v2
	s_waitcnt vmcnt(0)
	v_readfirstlane_b32 s2, v3
	v_sub_u32_e32 v3, 0, v2
	v_rcp_iflag_f32_e32 v4, v4
	v_add_u32_e32 v5, s2, v1
	v_mul_f32_e32 v4, 0x4f7ffffe, v4
	v_cvt_u32_f32_e32 v4, v4
	v_mul_lo_u32 v1, v3, v4
	v_mul_hi_u32 v1, v4, v1
	v_add_u32_e32 v1, v4, v1
	v_mul_hi_u32 v1, v5, v1
	v_mul_lo_u32 v3, v1, v2
	v_sub_u32_e32 v3, v5, v3
	v_add_u32_e32 v4, 1, v1
	v_cmp_ge_u32_e32 vcc, v3, v2
	s_nop 1
	v_cndmask_b32_e32 v1, v1, v4, vcc
	v_sub_u32_e32 v4, v3, v2
	v_cndmask_b32_e32 v3, v3, v4, vcc
	v_add_u32_e32 v4, 1, v1
	v_cmp_ge_u32_e32 vcc, v3, v2
	v_add_u32_e32 v3, 1, v5
	s_nop 0
	v_cndmask_b32_e32 v1, v1, v4, vcc
	v_mul_lo_u32 v4, v2, v1
	v_add_u32_e32 v2, v4, v2
	v_cmp_eq_u32_e32 vcc, v3, v2
	s_and_saveexec_b64 s[10:11], vcc
	s_cbranch_execz .Lfb_nl_3
	s_sub_u32 s100, s8, s6
	s_sub_u32 s100, s100, 0x4000
	s_lshr_b32 s100, s100, 6
	s_add_u32 s100, s100, 0x8000
	v_mov_b32_e32 v4, s100
	v_mov_b32_e32 v5, 1
	global_atomic_add v4, v5, s[6:7]

.Lfb_poll_3:
	global_load_dword v3, v2, s[6:7] sc1
	s_waitcnt vmcnt(0)
	v_cmp_le_u32_e32 vcc, s100, v3
	s_bcnt1_i32_b32 vcc_hi, vcc_lo
	s_cmp_ge_u32 vcc_hi, s101
	s_cbranch_scc1 .Lfb_done_3
	s_sleep 1
	s_add_u32 s10, s10, 1
	s_cmp_lt_u32 s10, 0x40000
	s_cbranch_scc1 .Lfb_poll_3

.LBB0_939:
	s_or_b64 exec, exec, s[12:13]
	v_cvt_f32_u32_e32 v4, v2
	s_waitcnt vmcnt(0)
	v_readfirstlane_b32 s2, v3
	v_sub_u32_e32 v3, 0, v2
	v_rcp_iflag_f32_e32 v4, v4
	v_add_u32_e32 v5, s2, v1
	v_mul_f32_e32 v4, 0x4f7ffffe, v4
	v_cvt_u32_f32_e32 v4, v4
	v_mul_lo_u32 v1, v3, v4
	v_mul_hi_u32 v1, v4, v1
	v_add_u32_e32 v1, v4, v1
	v_mul_hi_u32 v1, v5, v1
	v_mul_lo_u32 v3, v1, v2
	v_sub_u32_e32 v3, v5, v3
	v_add_u32_e32 v4, 1, v1
	v_cmp_ge_u32_e32 vcc, v3, v2
	s_nop 1
	v_cndmask_b32_e32 v1, v1, v4, vcc
	v_sub_u32_e32 v4, v3, v2
	v_cndmask_b32_e32 v3, v3, v4, vcc
	v_add_u32_e32 v4, 1, v1
	v_cmp_ge_u32_e32 vcc, v3, v2
	v_add_u32_e32 v3, 1, v5
	s_nop 0
	v_cndmask_b32_e32 v1, v1, v4, vcc
	v_mul_lo_u32 v4, v2, v1
	v_add_u32_e32 v2, v4, v2
	v_cmp_eq_u32_e32 vcc, v3, v2
	s_and_saveexec_b64 s[10:11], vcc
	s_cbranch_execz .Lfb_nl_4
	buffer_wbl2 sc1
	s_waitcnt vmcnt(0)
	s_sub_u32 s100, s8, s6
	s_sub_u32 s100, s100, 0x4000
	s_lshr_b32 s100, s100, 6
	s_add_u32 s100, s100, 0x8000
	v_mov_b32_e32 v4, s100
	v_mov_b32_e32 v5, 1
	global_atomic_add v4, v5, s[6:7]

.LBB0_1111:
	s_or_b64 exec, exec, s[14:15]
	v_cvt_f32_u32_e32 v4, v2
	s_waitcnt vmcnt(0)
	v_readfirstlane_b32 s2, v3
	v_sub_u32_e32 v3, 0, v2
	v_rcp_iflag_f32_e32 v4, v4
	v_add_u32_e32 v5, s2, v1
	v_mul_f32_e32 v4, 0x4f7ffffe, v4
	v_cvt_u32_f32_e32 v4, v4
	v_mul_lo_u32 v1, v3, v4
	v_mul_hi_u32 v1, v4, v1
	v_add_u32_e32 v1, v4, v1
	v_mul_hi_u32 v1, v5, v1
	v_mul_lo_u32 v3, v1, v2
	v_sub_u32_e32 v3, v5, v3
	v_add_u32_e32 v4, 1, v1
	v_cmp_ge_u32_e32 vcc, v3, v2
	s_nop 1
	v_cndmask_b32_e32 v1, v1, v4, vcc
	v_sub_u32_e32 v4, v3, v2
	v_cndmask_b32_e32 v3, v3, v4, vcc
	v_add_u32_e32 v4, 1, v1
	v_cmp_ge_u32_e32 vcc, v3, v2
	v_add_u32_e32 v3, 1, v5
	s_nop 0
	v_cndmask_b32_e32 v1, v1, v4, vcc
	v_mul_lo_u32 v4, v2, v1
	v_add_u32_e32 v2, v4, v2
	v_cmp_eq_u32_e32 vcc, v3, v2
	s_and_saveexec_b64 s[12:13], vcc
	s_cbranch_execz .Lfb_nl_5
	s_sub_u32 s100, s10, s6
	s_sub_u32 s100, s100, 0x4000
	s_lshr_b32 s100, s100, 6
	s_add_u32 s100, s100, 0x8000
	v_mov_b32_e32 v4, s100
	v_mov_b32_e32 v5, 1
	global_atomic_add v4, v5, s[6:7]

.Lfb_done_7:
	s_mov_b64 exec, 1
	s_branch .LBB0_334
